# attention score-accumulator preset: 15 v_mov_b32 splat replaced by 1 v_mov_b32 + 7 v_mov_b64 (5 sites)
# speedup vs baseline: 1.0130x; 1.0130x over previous
; __device__ __forceinline__ void diff_unit(int b, int hd, int qb, const bf16_t* Q, const bf16_t* K, const bf16_t* VT, bf16_t* O, const float* biasd, float lam, const float* subg, ALAS unsigned char* lds) {
;     ...
;     const int tid = tid_, lane = tid & 63, wid = __builtin_amdgcn_readfirstlane(tid >> 6), r32 = lane & 31, hi = lane >> 5;
;     const int map = wid >> 2, w4 = wid & 3, q0 = qb * 128 + w4 * 32, qpos = q0 + r32;
;     if (wid >= 4) __builtin_amdgcn_s_setprio(1);
;     const size_t tok0 = (size_t)b * SEQ;
;     ALAS float* btab = (ALAS float*)(lds + 73728);
;     btab[tid] = biasd[(2 * hd) * 256 + tid];
;     const ALAS float* bt = btab + map * 256;
;     const float cb = biasd[(2 * hd + map) * 256 + 255];
;     bf16x8 qf[4];
;     { const bf16_t* qp = Q + (tok0 + qpos) * 1024 + (2 * hd + map) * 64 + hi * 8;
; #pragma unroll
;       for (int d0 = 0; d0 < 4; ++d0) qf[d0] = *(const bf16x8*)(qp + d0 * 16); }
;     const int NT = 2 * (qb + 1);
;     const bf16_t* kg[2]; const bf16_t* vg[2]; int kl[2], vl[2];
; #pragma unroll
;     for (int i = 0; i < 2; ++i) { const int c = tid + 512 * i; const int key = c >> 4, part = c & 15;
;         kg[i] = K + (tok0 + key) * 1024 + hd * 128 + part * 8; kl[i] = ((part >> 3) * 64 + key) * ROWB + (part & 7) * 16;
;         const int d = c >> 3, pv = c & 7; vg[i] = VT + (size_t)(hd * 128 + d) * MTOK + tok0 + pv * 8; vl[i] = 18432 + d * ROWB + pv * 16; }
;     u32x4 kr[2], vr[2];
; #pragma unroll
;     for (int i = 0; i < 2; ++i) { kr[i] = *(const u32x4*)(kg[i]); vr[i] = *(const u32x4*)(vg[i]); }
;     f32x16 o[4]; float mref = 0.f, lsum = 0.f;
; #pragma unroll
;     for (int d = 0; d < 4; ++d)
; #pragma unroll
;         for (int r = 0; r < 16; ++r) o[d][r] = 0.f;
;     for (int t = 0; t < NT; ++t) {
;         ALAS unsigned char* buf = lds + (t & 1) * 36864;
; #pragma unroll
;         for (int i = 0; i < 2; ++i) { *(ALAS u32x4*)(buf + kl[i]) = kr[i]; *(ALAS u32x4*)(buf + vl[i]) = vr[i]; }
;         __syncthreads();
;         if (t + 1 < NT) {
; #pragma unroll
;             for (int i = 0; i < 2; ++i) { kr[i] = *(const u32x4*)(kg[i] + (size_t)(t + 1) * 64 * 1024); vr[i] = *(const u32x4*)(vg[i] + (t + 1) * 64); }
;         }
;         const int kbase = 64 * t;
;         if (kbase <= q0 + 31) {
;             const bool far = (q0 - (kbase + 63)) >= 128;
;             f32x16 s0, s1; const float ci = (far ? cb : 0.f) - mref;
.LBB0_497:
	s_ashr_i32 s9, s1, 6
	s_and_b32 s6, s1, 3
	s_and_b32 s9, s9, -8
	s_or_b32 s6, s9, s6
	s_and_b32 s8, s1, 0x100
	s_xor_b32 s9, s6, 7
	s_cmp_eq_u32 s8, 0
	s_cselect_b32 s14, s6, s9
	s_bfe_u32 s10, s1, 0x30002
	v_lshl_add_u32 v0, s10, 9, v135
	v_ashrrev_i32_e32 v1, 31, v0
	v_lshl_add_u64 v[0:1], v[0:1], 2, s[96:97]
	global_load_dword v26, v[0:1], off
	s_and_b32 s8, s4, 3
	s_lshl_b32 s12, s14, 7
	s_lshl_b32 s13, s8, 5
	v_and_b32_e32 v70, 31, v135
	s_or_b32 s15, s13, s12
	v_or_b32_e32 v136, s15, v70
	s_lshl_b32 s4, s1, 7
	v_lshl_add_u32 v27, v135, 2, 0
	s_and_b32 s4, s4, 0x7000
	v_add_u32_e32 v27, 0x12000, v27
	v_ashrrev_i32_e32 v137, 31, v136
	v_bfe_u32 v2, v135, 5, 1
	s_ashr_i32 s9, s7, 8
	s_lshl_b32 s6, s10, 7
	s_cmp_lt_i32 s14, 0
	v_lshlrev_b32_e32 v134, 3, v2
	v_lshlrev_b32_e32 v130, 4, v2
	v_lshrrev_b32_e32 v28, 8, v135
	v_lshl_add_u32 v28, v28, 10, v27
	v_lshl_add_u64 v[0:1], v[136:137], 0, s[4:5]
	v_lshlrev_b64 v[132:133], 10, v[0:1]
	s_cbranch_scc1 .LBB0_511
	s_lshl_b32 s10, s10, 1
	s_add_i32 s17, s9, s10
	s_lshl_b32 s10, s17, 8
	s_ashr_i32 s11, s10, 31
	s_and_b32 s16, s7, 0x3fffff00
	s_lshl_b64 s[10:11], s[10:11], 2
	s_add_u32 s10, s96, s10
	s_addc_u32 s11, s97, s11
	global_load_dword v137, v145, s[10:11] offset:1020
	s_lshl_b32 s10, s6, 1
	s_add_u32 s10, s82, s10
	v_lshlrev_b32_e32 v1, 4, v135
	s_addc_u32 s11, s83, 0
	v_and_b32_e32 v144, 0xf0, v1
	v_lshlrev_b32_e32 v0, 3, v135
	v_lshl_add_u64 v[2:3], s[10:11], 0, v[144:145]
	s_lshl_b32 s10, s4, 1
	v_and_b32_e32 v8, 64, v0
	s_add_u32 s10, s20, s10
	v_ashrrev_i32_e32 v64, 4, v135
	v_and_b32_e32 v20, 0x70, v1
	s_addc_u32 s11, s21, 0
	v_mov_b32_e32 v21, v145
	v_add_u32_e32 v6, v8, v64
	s_movk_i32 s18, 0x90
	v_lshl_add_u64 v[4:5], s[10:11], 0, v[20:21]
	v_mad_u64_u32 v[138:139], s[10:11], v6, s18, v[20:21]
	v_ashrrev_i32_e32 v21, 3, v135
	v_add_u32_e32 v6, s6, v21
	v_add_u32_e32 v9, 0x200, v135
	v_ashrrev_i32_e32 v7, 31, v6
	v_ashrrev_i32_e32 v66, 4, v9
	v_ashrrev_i32_e32 v65, 31, v64
	v_lshlrev_b64 v[6:7], 16, v[6:7]
	v_ashrrev_i32_e32 v67, 31, v66
	v_lshl_add_u64 v[0:1], v[64:65], 0, s[4:5]
	v_lshl_add_u64 v[140:141], v[4:5], 0, v[6:7]
	v_lshl_add_u64 v[6:7], v[66:67], 0, s[4:5]
	v_lshlrev_b64 v[0:1], 11, v[0:1]
	v_lshlrev_b64 v[6:7], 11, v[6:7]
	v_lshl_add_u64 v[0:1], v[2:3], 0, v[0:1]
	v_lshl_add_u64 v[2:3], v[2:3], 0, v[6:7]
	v_add_u32_e32 v6, v66, v8
	v_ashrrev_i32_e32 v22, 3, v9
	v_mad_u64_u32 v[142:143], s[10:11], v6, s18, v[20:21]
	v_add_u32_e32 v6, s6, v22
	v_ashrrev_i32_e32 v7, 31, v6
	v_lshlrev_b64 v[6:7], 16, v[6:7]
	s_lshl_b32 s4, s16, 2
	s_lshl_b32 s16, s17, 6
	v_lshl_add_u64 v[156:157], v[4:5], 0, v[6:7]
	v_lshl_add_u64 v[4:5], v[132:133], 1, s[80:81]
	s_ashr_i32 s17, s16, 31
	v_lshl_add_u64 v[4:5], s[16:17], 1, v[4:5]
	v_mov_b32_e32 v131, v145
	v_lshl_add_u64 v[4:5], v[4:5], 0, v[130:131]
	global_load_dwordx4 v[96:99], v[4:5], off offset:96
	global_load_dwordx4 v[100:103], v[4:5], off offset:64
	global_load_dwordx4 v[104:107], v[4:5], off offset:32
	global_load_dwordx4 v[108:111], v[4:5], off
	s_nop 0
	global_load_dwordx4 v[4:7], v[156:157], off
	global_load_dwordx4 v[8:11], v[2:3], off
	global_load_dwordx4 v[12:15], v[140:141], off
	global_load_dwordx4 v[16:19], v[0:1], off
	v_lshlrev_b32_e32 v24, 1, v70
	v_lshrrev_b32_e32 v25, 1, v135
	v_and_b32_e32 v23, 19, v135
	v_and_b32_e32 v24, 8, v24
	v_and_b32_e32 v25, 4, v25
	v_or3_b32 v23, v25, v23, v24
	v_mul_u32_u24_e32 v139, 0x90, v23
	v_add_u32_e32 v23, 0, v138
	v_mad_u64_u32 v[158:159], s[16:17], v21, s18, v[20:21]
	s_add_i32 s10, s4, 0
	s_mov_b32 s4, 0x20000
	v_mad_u64_u32 v[160:161], s[16:17], v22, s18, v[20:21]
	v_add_co_u32_e32 v0, vcc, s4, v0
	s_add_i32 s10, s10, 0x12000
	s_nop 0
	v_addc_co_u32_e32 v1, vcc, 0, v1, vcc
	s_mul_i32 s11, s9, 0x2400
	s_cmpk_gt_i32 s15, 0xbe
	s_waitcnt vmcnt(0)
	ds_write_b32 v27, v26
	ds_write_b32 v28, v26 offset:3072
	ds_write_b32 v28, v205 offset:2048
	ds_write_b128 v23, v[16:19]
	v_add_u32_e32 v16, 0, v158
	ds_write_b128 v16, v[12:15] offset:18432
	v_add_u32_e32 v12, 0, v142
	ds_write_b128 v12, v[8:11]
	v_add_u32_e32 v8, 0, v160
	ds_write_b128 v8, v[4:7] offset:18432
	s_waitcnt lgkmcnt(0)
	s_barrier
	global_load_dwordx4 v[112:115], v[0:1], off
	global_load_dwordx4 v[116:119], v[140:141], off offset:128
	v_add_co_u32_e32 v0, vcc, s4, v2
	s_nop 1
	v_addc_co_u32_e32 v1, vcc, 0, v3, vcc
	global_load_dwordx4 v[120:123], v[0:1], off
	global_load_dwordx4 v[124:127], v[156:157], off offset:128
	s_cselect_b64 vcc, -1, 0
	s_add_i32 s4, s11, 0
	v_add3_u32 v1, s4, v139, v130
	ds_read_b128 v[32:35], v1 offset:0
	ds_read_b128 v[36:39], v1 offset:4608
	ds_read_b128 v[40:43], v1 offset:32
	ds_read_b128 v[44:47], v1 offset:4640
	ds_read_b128 v[48:51], v1 offset:64
	ds_read_b128 v[52:55], v1 offset:4672
	ds_read_b128 v[56:59], v1 offset:96
	ds_read_b128 v[60:63], v1 offset:4704
	v_cndmask_b32_e32 v0, 0, v137, vcc
	v_mov_b32_e32 v1, v0
	v_mov_b64_e32 v[2:3], v[0:1]
	v_mov_b64_e32 v[4:5], v[0:1]
	v_mov_b64_e32 v[6:7], v[0:1]
	v_mov_b64_e32 v[8:9], v[0:1]
	v_mov_b64_e32 v[10:11], v[0:1]
	v_mov_b64_e32 v[12:13], v[0:1]
	v_mov_b64_e32 v[14:15], v[0:1]
	s_waitcnt lgkmcnt(6)
	s_nop 1
	v_mfma_f32_32x32x16_bf16 v[16:31], v[32:35], v[108:111], v[0:15]
	s_and_b64 vcc, exec, vcc
	v_mfma_f32_32x32x16_bf16 v[0:15], v[36:39], v[108:111], v[0:15]
	s_waitcnt lgkmcnt(4)
	v_mfma_f32_32x32x16_bf16 v[16:31], v[40:43], v[104:107], v[16:31]
	v_mfma_f32_32x32x16_bf16 v[0:15], v[44:47], v[104:107], v[0:15]
	s_waitcnt lgkmcnt(2)
	v_mfma_f32_32x32x16_bf16 v[16:31], v[48:51], v[100:103], v[16:31]
	v_mfma_f32_32x32x16_bf16 v[0:15], v[52:55], v[100:103], v[0:15]
	s_waitcnt lgkmcnt(0)
	v_mfma_f32_32x32x16_bf16 v[16:31], v[56:59], v[96:99], v[16:31]
	v_mfma_f32_32x32x16_bf16 v[0:15], v[60:63], v[96:99], v[0:15]
	s_cbranch_vccnz .LBB0_500
; #define ALAS __attribute__((address_space(3)))
; __device__ __forceinline__ void near_bias(f32x16& s0, f32x16& s1, const ALAS float* bt, int qpos, int kbase, int hi) {
; #pragma unroll
;     for (int r = 0; r < 16; ++r) {
;         const int d0 = qpos - (kbase + (r & 7) + 8 * hi + 16 * (r >> 3)), d1 = d0 - 32;
;         const float b0 = bt[min(max(d0, 0), 255)], b1 = bt[min(max(d1, 0), 255)];
;         s0[r] = d0 < 0 ? NEG : s0[r] + b0; s1[r] = d1 < 0 ? NEG : s1[r] + b1;
;     }
; }
	v_xad_u32 v69, v134, -1, v136
	v_med3_i32 v34, v69, 0, v204
	v_lshl_add_u32 v35, v34, 2, s10
	v_max_i32_e32 v34, 32, v69
	v_subrev_u32_e32 v34, 32, v34
	v_min_u32_e32 v34, 0xff, v34
	v_or_b32_e32 v37, 2, v134
	v_lshl_add_u32 v36, v34, 2, s10
	v_or_b32_e32 v34, 3, v134
	v_sub_u32_e32 v72, v136, v37
	v_sub_u32_e32 v71, v136, v34
	v_med3_i32 v34, v72, 0, v204
	v_lshl_add_u32 v37, v34, 2, s10
	v_max_i32_e32 v34, 32, v72
	v_subrev_u32_e32 v34, 32, v34
	v_min_u32_e32 v34, 0xff, v34
	v_sub_u32_e32 v68, v136, v134
	v_lshl_add_u32 v38, v34, 2, s10
	v_max_i32_e32 v34, 32, v71
	v_max_i32_e32 v33, 32, v68
	v_subrev_u32_e32 v34, 32, v34
	v_subrev_u32_e32 v33, 32, v33
	v_min_u32_e32 v34, 0xff, v34
	v_med3_i32 v32, v68, 0, v204
	v_min_u32_e32 v33, 0xff, v33
	v_lshl_add_u32 v39, v34, 2, s10
	v_med3_i32 v34, v71, 0, v204
	v_lshl_add_u32 v32, v32, 2, s10
	v_lshl_add_u32 v33, v33, 2, s10
	v_lshl_add_u32 v40, v34, 2, s10
	ds_read_b32 v34, v32
	ds_read_b32 v32, v33
	ds_read_b32 v35, v35
	ds_read_b32 v33, v36
	ds_read_b32 v36, v37
	ds_read_b32 v38, v38
	ds_read_b32 v39, v39
	ds_read_b32 v37, v40
	v_or_b32_e32 v40, 5, v134
	v_sub_u32_e32 v73, v136, v40
	v_max_i32_e32 v42, 32, v73
	v_subrev_u32_e32 v42, 32, v42
	v_min_u32_e32 v42, 0xff, v42
	v_lshl_add_u32 v43, v42, 2, s10
	v_med3_i32 v42, v73, 0, v204
	v_or_b32_e32 v45, 6, v134
	v_lshl_add_u32 v44, v42, 2, s10
	v_or_b32_e32 v42, 7, v134
	v_sub_u32_e32 v76, v136, v45
	v_sub_u32_e32 v75, v136, v42
	v_med3_i32 v42, v76, 0, v204
	v_lshl_add_u32 v45, v42, 2, s10
	v_max_i32_e32 v42, 32, v76
	v_subrev_u32_e32 v42, 32, v42
	v_or_b32_e32 v41, 4, v134
	v_min_u32_e32 v42, 0xff, v42
	v_sub_u32_e32 v74, v136, v41
	v_lshl_add_u32 v46, v42, 2, s10
	v_max_i32_e32 v42, 32, v75
	v_max_i32_e32 v41, 32, v74
	v_subrev_u32_e32 v42, 32, v42
	v_subrev_u32_e32 v41, 32, v41
	v_min_u32_e32 v42, 0xff, v42
	v_med3_i32 v40, v74, 0, v204
	v_min_u32_e32 v41, 0xff, v41
	v_lshl_add_u32 v47, v42, 2, s10
	v_med3_i32 v42, v75, 0, v204
	v_lshl_add_u32 v40, v40, 2, s10
	v_lshl_add_u32 v41, v41, 2, s10
	v_lshl_add_u32 v48, v42, 2, s10
	ds_read_b32 v40, v40
	ds_read_b32 v42, v41
	ds_read_b32 v43, v43
	ds_read_b32 v41, v44
	ds_read_b32 v44, v45
	ds_read_b32 v46, v46
	ds_read_b32 v47, v47
	ds_read_b32 v45, v48
	v_or_b32_e32 v48, 17, v134
	v_sub_u32_e32 v77, v136, v48
	v_max_i32_e32 v50, 32, v77
	v_subrev_u32_e32 v50, 32, v50
	v_min_u32_e32 v50, 0xff, v50
	v_lshl_add_u32 v51, v50, 2, s10
	v_med3_i32 v50, v77, 0, v204
	v_or_b32_e32 v53, 18, v134
	v_lshl_add_u32 v52, v50, 2, s10
	v_or_b32_e32 v50, 19, v134
	v_sub_u32_e32 v80, v136, v53
	v_sub_u32_e32 v79, v136, v50
	v_med3_i32 v50, v80, 0, v204
	v_lshl_add_u32 v53, v50, 2, s10
	v_max_i32_e32 v50, 32, v80
	v_subrev_u32_e32 v50, 32, v50
	v_or_b32_e32 v49, 16, v134
	v_min_u32_e32 v50, 0xff, v50
	v_sub_u32_e32 v78, v136, v49
	v_lshl_add_u32 v54, v50, 2, s10
	v_max_i32_e32 v50, 32, v79
	v_max_i32_e32 v49, 32, v78
	v_subrev_u32_e32 v50, 32, v50
	v_subrev_u32_e32 v49, 32, v49
	v_min_u32_e32 v50, 0xff, v50
	v_med3_i32 v48, v78, 0, v204
	v_min_u32_e32 v49, 0xff, v49
	v_lshl_add_u32 v55, v50, 2, s10
	v_med3_i32 v50, v79, 0, v204
	v_lshl_add_u32 v48, v48, 2, s10
	v_lshl_add_u32 v49, v49, 2, s10
	v_lshl_add_u32 v56, v50, 2, s10
	ds_read_b32 v48, v48
	ds_read_b32 v50, v49
	ds_read_b32 v51, v51
	ds_read_b32 v49, v52
	ds_read_b32 v52, v53
	ds_read_b32 v54, v54
	ds_read_b32 v55, v55
	ds_read_b32 v53, v56
	v_or_b32_e32 v56, 21, v134
	v_sub_u32_e32 v81, v136, v56
	v_max_i32_e32 v58, 32, v81
	v_subrev_u32_e32 v58, 32, v58
	v_min_u32_e32 v58, 0xff, v58
	v_lshl_add_u32 v59, v58, 2, s10
	v_med3_i32 v58, v81, 0, v204
	v_or_b32_e32 v61, 22, v134
	v_lshl_add_u32 v60, v58, 2, s10
	v_or_b32_e32 v58, 23, v134
	v_sub_u32_e32 v84, v136, v61
	v_sub_u32_e32 v83, v136, v58
	v_med3_i32 v58, v84, 0, v204
	v_lshl_add_u32 v61, v58, 2, s10
	v_max_i32_e32 v58, 32, v84
	v_or_b32_e32 v57, 20, v134
	v_subrev_u32_e32 v58, 32, v58
	v_sub_u32_e32 v82, v136, v57
	v_min_u32_e32 v58, 0xff, v58
	v_max_i32_e32 v57, 32, v82
	v_lshl_add_u32 v62, v58, 2, s10
	v_max_i32_e32 v58, 32, v83
	v_subrev_u32_e32 v57, 32, v57
	v_subrev_u32_e32 v58, 32, v58
	v_med3_i32 v56, v82, 0, v204
	v_min_u32_e32 v57, 0xff, v57
	v_min_u32_e32 v58, 0xff, v58
	v_lshl_add_u32 v56, v56, 2, s10
	v_lshl_add_u32 v57, v57, 2, s10
	v_lshl_add_u32 v63, v58, 2, s10
	v_med3_i32 v58, v83, 0, v204
	v_lshl_add_u32 v85, v58, 2, s10
	ds_read_b32 v56, v56
	ds_read_b32 v58, v57
	ds_read_b32 v59, v59
	ds_read_b32 v57, v60
	ds_read_b32 v60, v61
	ds_read_b32 v62, v62
	ds_read_b32 v63, v63
	ds_read_b32 v61, v85
	s_waitcnt lgkmcnt(14)
; #define ALAS __attribute__((address_space(3)))
; __device__ __forceinline__ void near_bias(f32x16& s0, f32x16& s1, const ALAS float* bt, int qpos, int kbase, int hi) {
; #pragma unroll
;     for (int r = 0; r < 16; ++r) {
;         const int d0 = qpos - (kbase + (r & 7) + 8 * hi + 16 * (r >> 3)), d1 = d0 - 32;
;         const float b0 = bt[min(max(d0, 0), 255)], b1 = bt[min(max(d1, 0), 255)];
;         s0[r] = d0 < 0 ? NEG : s0[r] + b0; s1[r] = d1 < 0 ? NEG : s1[r] + b1;
;     }
; }
	v_pk_add_f32 v[16:17], v[16:17], v[34:35]
	v_cmp_lt_i32_e32 vcc, -1, v69
	s_waitcnt lgkmcnt(4)
	v_pk_add_f32 v[28:29], v[28:29], v[56:57]
	v_pk_add_f32 v[26:27], v[26:27], v[52:53]
	s_waitcnt lgkmcnt(0)
	v_pk_add_f32 v[30:31], v[30:31], v[60:61]
	v_cndmask_b32_e32 v17, v205, v17, vcc
	v_cmp_lt_i32_e32 vcc, -1, v83
	v_pk_add_f32 v[24:25], v[24:25], v[48:49]
	v_pk_add_f32 v[22:23], v[22:23], v[44:45]
	v_cndmask_b32_e32 v31, v205, v31, vcc
	v_cmp_lt_i32_e32 vcc, -1, v84
	v_pk_add_f32 v[20:21], v[20:21], v[40:41]
	v_pk_add_f32 v[18:19], v[18:19], v[36:37]
	v_cndmask_b32_e32 v30, v205, v30, vcc
	v_cmp_lt_i32_e32 vcc, -1, v81
	v_pk_add_f32 v[0:1], v[0:1], v[32:33]
	v_pk_add_f32 v[14:15], v[14:15], v[62:63]
	v_cndmask_b32_e32 v29, v205, v29, vcc
	v_cmp_lt_i32_e32 vcc, -1, v82
	v_pk_add_f32 v[12:13], v[12:13], v[58:59]
	v_pk_add_f32 v[10:11], v[10:11], v[54:55]
	v_cndmask_b32_e32 v28, v205, v28, vcc
	v_cmp_lt_i32_e32 vcc, -1, v79
	v_pk_add_f32 v[8:9], v[8:9], v[50:51]
	v_pk_add_f32 v[6:7], v[6:7], v[46:47]
	v_cndmask_b32_e32 v27, v205, v27, vcc
	v_cmp_lt_i32_e32 vcc, -1, v80
	v_pk_add_f32 v[4:5], v[4:5], v[42:43]
	v_pk_add_f32 v[2:3], v[2:3], v[38:39]
	v_cndmask_b32_e32 v26, v205, v26, vcc
	v_cmp_lt_i32_e32 vcc, -1, v77
	s_nop 1
	v_cndmask_b32_e32 v25, v205, v25, vcc
	v_cmp_lt_i32_e32 vcc, -1, v78
	s_nop 1
	v_cndmask_b32_e32 v24, v205, v24, vcc
	v_cmp_lt_i32_e32 vcc, -1, v75
	s_nop 1
	v_cndmask_b32_e32 v23, v205, v23, vcc
	v_cmp_lt_i32_e32 vcc, -1, v76
	s_nop 1
	v_cndmask_b32_e32 v22, v205, v22, vcc
	v_cmp_lt_i32_e32 vcc, -1, v73
	s_nop 1
	v_cndmask_b32_e32 v21, v205, v21, vcc
	v_cmp_lt_i32_e32 vcc, -1, v74
	s_nop 1
	v_cndmask_b32_e32 v20, v205, v20, vcc
	v_cmp_lt_i32_e32 vcc, -1, v71
	s_nop 1
	v_cndmask_b32_e32 v19, v205, v19, vcc
	v_cmp_lt_i32_e32 vcc, -1, v72
	s_nop 1
	v_cndmask_b32_e32 v18, v205, v18, vcc
	v_cmp_lt_i32_e32 vcc, -1, v68
	s_nop 1
	v_cndmask_b32_e32 v16, v205, v16, vcc
	v_cmp_lt_i32_e32 vcc, 31, v69
	s_nop 1
	v_cndmask_b32_e32 v1, v205, v1, vcc
	v_cmp_lt_i32_e32 vcc, 31, v83
	s_nop 1
	v_cndmask_b32_e32 v15, v205, v15, vcc
	v_cmp_lt_i32_e32 vcc, 31, v84
	s_nop 1
	v_cndmask_b32_e32 v14, v205, v14, vcc
	v_cmp_lt_i32_e32 vcc, 31, v81
	s_nop 1
	v_cndmask_b32_e32 v13, v205, v13, vcc
	v_cmp_lt_i32_e32 vcc, 31, v82
	s_nop 1
	v_cndmask_b32_e32 v12, v205, v12, vcc
	v_cmp_lt_i32_e32 vcc, 31, v79
	s_nop 1
	v_cndmask_b32_e32 v11, v205, v11, vcc
	v_cmp_lt_i32_e32 vcc, 31, v80
	s_nop 1
	v_cndmask_b32_e32 v10, v205, v10, vcc
	v_cmp_lt_i32_e32 vcc, 31, v77
	s_nop 1
	v_cndmask_b32_e32 v9, v205, v9, vcc
	v_cmp_lt_i32_e32 vcc, 31, v78
	s_nop 1
	v_cndmask_b32_e32 v8, v205, v8, vcc
	v_cmp_lt_i32_e32 vcc, 31, v75
	s_nop 1
	v_cndmask_b32_e32 v7, v205, v7, vcc
	v_cmp_lt_i32_e32 vcc, 31, v76
	s_nop 1
	v_cndmask_b32_e32 v6, v205, v6, vcc
	v_cmp_lt_i32_e32 vcc, 31, v73
	s_nop 1
	v_cndmask_b32_e32 v5, v205, v5, vcc
	v_cmp_lt_i32_e32 vcc, 31, v74
	s_nop 1
	v_cndmask_b32_e32 v4, v205, v4, vcc
	v_cmp_lt_i32_e32 vcc, 31, v71
	s_nop 1
	v_cndmask_b32_e32 v3, v205, v3, vcc
	v_cmp_lt_i32_e32 vcc, 31, v72
	s_nop 1
	v_cndmask_b32_e32 v2, v205, v2, vcc
	v_cmp_lt_i32_e32 vcc, 31, v68
	s_nop 1
	v_cndmask_b32_e32 v0, v205, v0, vcc

; #define ALAS __attribute__((address_space(3)))
; __device__ __forceinline__ int kperm(int i) { return (i & 19) | ((i & 4) << 1) | ((i & 8) >> 1); }
; template <int OFF> __device__ __forceinline__ void ldsr(bf16x8& d, unsigned a) { asm volatile("ds_read_b128 %0, %1 offset:%c2" : "=v"(d) : "v"(a), "i"(OFF) : "memory"); }
; __device__ __forceinline__ void lds_wait8(bf16x8 (&a)[8]) { asm volatile("s_waitcnt lgkmcnt(0)" : "+v"(a[0]), "+v"(a[1]), "+v"(a[2]), "+v"(a[3]), "+v"(a[4]), "+v"(a[5]), "+v"(a[6]), "+v"(a[7]) :: "memory"); }
; __device__ __forceinline__ void qk_tile(f32x16& s0, f32x16& s1, float ci, const ALAS unsigned char* Kb, const bf16x8 (&qf)[4], int r32, int hi) {
;     const unsigned p0 = (unsigned)(uintptr_t)(Kb + kperm(r32) * ROWB + hi * 16);
;     bf16x8 a[8];
;     ldsr<0>(a[0], p0); ldsr<32 * ROWB>(a[1], p0); ldsr<32>(a[2], p0); ldsr<32 * ROWB + 32>(a[3], p0);
;     ldsr<64>(a[4], p0); ldsr<32 * ROWB + 64>(a[5], p0); ldsr<96>(a[6], p0); ldsr<32 * ROWB + 96>(a[7], p0);
; #pragma unroll
;     for (int r = 0; r < 16; ++r) { s0[r] = ci; s1[r] = ci; }
;     lds_wait8(a); __builtin_amdgcn_sched_barrier(0);
; #pragma unroll
;     for (int d0 = 0; d0 < 4; ++d0) {
;         s0 = __builtin_amdgcn_mfma_f32_32x32x16_bf16(a[2 * d0], qf[d0], s0, 0, 0, 0);
;         s1 = __builtin_amdgcn_mfma_f32_32x32x16_bf16(a[2 * d0 + 1], qf[d0], s1, 0, 0, 0);
;     }
; __device__ __forceinline__ void diff_unit(int b, int hd, int qb, const bf16_t* Q, const bf16_t* K, const bf16_t* VT, bf16_t* O, const float* biasd, float lam, const float* subg, ALAS unsigned char* lds) {
;     ...
;         if (kbase <= q0 + 31) {
;             const bool far = (q0 - (kbase + 63)) >= 128;
;             f32x16 s0, s1; const float ci = (far ? cb : 0.f) - mref;
;             qk_tile(s0, s1, ci, buf + map * 9216, qf, r32, hi);
;             if (!far) near_bias(s0, s1, bt, qpos, kbase, hi);
.LBB0_506:
	s_cmp_gt_i32 s17, s15
	s_cbranch_scc1 .LBB0_503
	s_cmpk_gt_i32 s12, 0x7f
	s_cselect_b64 vcc, -1, 0
	s_nop 1
	v_cndmask_b32_e32 v64, 0, v137, vcc
	v_sub_f32_e32 v64, v64, v163
	v_mov_b32_e32 v65, v64
	v_mov_b64_e32 v[66:67], v[64:65]
	v_mov_b64_e32 v[68:69], v[64:65]
	v_mov_b64_e32 v[70:71], v[64:65]
	v_mov_b64_e32 v[72:73], v[64:65]
	v_mov_b64_e32 v[74:75], v[64:65]
	v_mov_b64_e32 v[76:77], v[64:65]
	v_mov_b64_e32 v[78:79], v[64:65]
	s_waitcnt lgkmcnt(6)
	s_nop 1
	v_mfma_f32_32x32x16_bf16 v[80:95], v[172:175], v[108:111], v[64:79]
	s_and_b64 vcc, exec, vcc
	v_mfma_f32_32x32x16_bf16 v[64:79], v[176:179], v[108:111], v[64:79]
	s_waitcnt lgkmcnt(4)
	v_mfma_f32_32x32x16_bf16 v[80:95], v[180:183], v[104:107], v[80:95]
	v_mfma_f32_32x32x16_bf16 v[64:79], v[184:187], v[104:107], v[64:79]
	s_waitcnt lgkmcnt(2)
	v_mfma_f32_32x32x16_bf16 v[80:95], v[188:191], v[100:103], v[80:95]
	v_mfma_f32_32x32x16_bf16 v[64:79], v[192:195], v[100:103], v[64:79]
	s_waitcnt lgkmcnt(0)
	v_mfma_f32_32x32x16_bf16 v[80:95], v[196:199], v[96:99], v[80:95]
	v_mfma_f32_32x32x16_bf16 v[64:79], v[216:219], v[96:99], v[64:79]
	s_cbranch_vccnz .LBB0_509
	v_add_u32_e32 v161, s12, v159
	v_lshlrev_b32_e32 v161, 2, v161
	s_lshl_b32 s4, s9, 11
	s_add_i32 s4, s4, 0x12c20
	v_add_u32_e32 v161, s4, v161
	ds_read_b32 v172, v161 offset:92
	ds_read_b32 v173, v161 offset:88
	ds_read_b32 v174, v161 offset:84
	ds_read_b32 v175, v161 offset:80
	ds_read_b32 v176, v161 offset:76
	ds_read_b32 v177, v161 offset:72
	ds_read_b32 v178, v161 offset:68
	ds_read_b32 v179, v161 offset:64
	ds_read_b32 v180, v161 offset:28
	ds_read_b32 v181, v161 offset:24
	ds_read_b32 v182, v161 offset:20
	ds_read_b32 v183, v161 offset:16
	ds_read_b32 v184, v161 offset:12
	ds_read_b32 v185, v161 offset:8
	ds_read_b32 v186, v161 offset:4
	ds_read_b32 v187, v161 offset:0
	ds_read_b32 v188, v161 offset:220
	ds_read_b32 v189, v161 offset:216
	ds_read_b32 v190, v161 offset:212
	ds_read_b32 v191, v161 offset:208
	ds_read_b32 v192, v161 offset:204
	ds_read_b32 v193, v161 offset:200
	ds_read_b32 v194, v161 offset:196
	ds_read_b32 v195, v161 offset:192
	ds_read_b32 v196, v161 offset:156
	ds_read_b32 v197, v161 offset:152
	ds_read_b32 v198, v161 offset:148
	ds_read_b32 v199, v161 offset:144
	ds_read_b32 v216, v161 offset:140
	ds_read_b32 v217, v161 offset:136
	ds_read_b32 v218, v161 offset:132
	ds_read_b32 v219, v161 offset:128
	s_waitcnt lgkmcnt(0)
	v_add_f32_e32 v64, v64, v172
	v_add_f32_e32 v65, v65, v173
	v_add_f32_e32 v66, v66, v174
	v_add_f32_e32 v67, v67, v175
	v_add_f32_e32 v68, v68, v176
	v_add_f32_e32 v69, v69, v177
	v_add_f32_e32 v70, v70, v178
	v_add_f32_e32 v71, v71, v179
	v_add_f32_e32 v72, v72, v180
	v_add_f32_e32 v73, v73, v181
	v_add_f32_e32 v74, v74, v182
	v_add_f32_e32 v75, v75, v183
	v_add_f32_e32 v76, v76, v184
	v_add_f32_e32 v77, v77, v185
	v_add_f32_e32 v78, v78, v186
	v_add_f32_e32 v79, v79, v187
	v_add_f32_e32 v80, v80, v188
	v_add_f32_e32 v81, v81, v189
	v_add_f32_e32 v82, v82, v190
	v_add_f32_e32 v83, v83, v191
	v_add_f32_e32 v84, v84, v192
	v_add_f32_e32 v85, v85, v193
	v_add_f32_e32 v86, v86, v194
	v_add_f32_e32 v87, v87, v195
	v_add_f32_e32 v88, v88, v196
	v_add_f32_e32 v89, v89, v197
	v_add_f32_e32 v90, v90, v198
	v_add_f32_e32 v91, v91, v199
	v_add_f32_e32 v92, v92, v216
	v_add_f32_e32 v93, v93, v217
	v_add_f32_e32 v94, v94, v218
	v_add_f32_e32 v95, v95, v219

; #define ALAS __attribute__((address_space(3)))
; __device__ __forceinline__ void moba_unit(int b, int h, int j, const bf16_t* Q, const bf16_t* K, const bf16_t* VT, bf16_t* O, const float* biasd, const float* kmean, ALAS unsigned char* lds) {
;     ...
;     { const int n = tid >> 5, d2 = (tid & 31) * 2; const float* kmp = kmean + (size_t)(b * 16 + n) * 2048 + h * 64 + d2; const float v0 = kmp[0] + kmp[1024], v1 = kmp[1] + kmp[1025];
;       const unsigned wh = cvtpk(v0, v1); const float h0 = __uint_as_float(wh << 16), h1 = __uint_as_float(wh & 0xffff0000u); const unsigned wl = cvtpk(v0 - h0, v1 - h1);
;       *(ALAS unsigned*)(lds + 37888 + n * ROWB + d2 * 2) = wh; *(ALAS unsigned*)(lds + 40192 + n * ROWB + d2 * 2) = wl; }
;     bf16x8 qf[4];
;     { const bf16_t* qp = Q + (tok0 + qpos) * 1024 + h * 64 + hi * 8;
; #pragma unroll
;       for (int d0 = 0; d0 < 4; ++d0) qf[d0] = *(const bf16x8*)(qp + d0 * 16); }
;     const int NT = 4 * (j + 1);
;     const int key = tid >> 3, part = tid & 7;
;     const bf16_t* kg = K + (tok0 + key) * 1024 + h * 64 + part * 8; const int kl = key * ROWB + part * 16;
;     const bf16_t* vg = VT + (size_t)(h * 64 + key) * MTOK + tok0 + part * 8; const int vl = 9216 + key * ROWB + part * 16;
;     u32x4 kr, vr;
;     { const int kb0 = 256 * j; kr = *(const u32x4*)(kg + (size_t)kb0 * 1024); vr = *(const u32x4*)(vg + kb0); }
;     __syncthreads();
;     unsigned selmask = 0u;
;     {
;         f32x16 g;
; #pragma unroll
;         for (int r = 0; r < 16; ++r) g[r] = 0.f;
;         const ALAS unsigned char* kp = lds + 37888 + (r32 & 15) * ROWB + hi * 16;
; #pragma unroll
;         for (int d0 = 0; d0 < 4; ++d0) {
;             const bf16x8 ah = *(const ALAS bf16x8*)(kp + d0 * 32), al = *(const ALAS bf16x8*)(kp + 2304 + d0 * 32);
;             g = __builtin_amdgcn_mfma_f32_32x32x16_bf16(ah, qf[d0], g, 0, 0, 0);
;             g = __builtin_amdgcn_mfma_f32_32x32x16_bf16(al, qf[d0], g, 0, 0, 0);
;     ...
;     for (int t = 0; t < NT; ++t) {
;         ALAS unsigned char* buf = lds + (t & 1) * 18432;
;         *(ALAS u32x4*)(buf + kl) = kr; *(ALAS u32x4*)(buf + vl) = vr;
;         __syncthreads();
;         if (t + 1 < NT) { const int t1 = t + 1; const int kb1 = (t1 < 4) ? (256 * j + 64 * t1) : (64 * (t1 - 4));
;             kr = *(const u32x4*)(kg + (size_t)kb1 * 1024); vr = *(const u32x4*)(vg + kb1); }
.Lmoba_bias_done:
	s_cmp_lt_i32 s37, 0
	v_pk_add_f32 v[12:13], v[12:13], v[14:15]
	s_nop 0
	v_cvt_pk_bf16_f32 v16, v12, v13
	v_lshlrev_b32_e32 v14, 16, v16
	v_and_b32_e32 v15, 0xffff0000, v16
	v_pk_add_f32 v[12:13], v[12:13], v[14:15] neg_lo:[0,1] neg_hi:[0,1]
	s_nop 0
	v_cvt_pk_bf16_f32 v12, v12, v13
	ds_write2st64_b32 v9, v16, v12 offset0:148 offset1:157
	s_waitcnt lgkmcnt(0)
	s_barrier
	ds_read_b128 v[12:15], v20 offset:37888
	s_waitcnt vmcnt(6) lgkmcnt(0)
	v_mfma_f32_32x32x16_bf16 v[32:47], v[12:15], v[64:67], 0
	ds_read_b128 v[12:15], v20 offset:40192
	v_xor_b32_e32 v9, 32, v203
	s_waitcnt lgkmcnt(0)
	v_mfma_f32_32x32x16_bf16 v[32:47], v[12:15], v[64:67], v[32:47]
	ds_read_b128 v[12:15], v20 offset:37920
	s_waitcnt vmcnt(5) lgkmcnt(0)
	v_mfma_f32_32x32x16_bf16 v[32:47], v[12:15], v[68:71], v[32:47]
	ds_read_b128 v[12:15], v20 offset:40224
	s_waitcnt lgkmcnt(0)
	v_mfma_f32_32x32x16_bf16 v[32:47], v[12:15], v[68:71], v[32:47]
	ds_read_b128 v[12:15], v20 offset:37952
	ds_read_b128 v[16:19], v20 offset:40256
	s_waitcnt vmcnt(4) lgkmcnt(1)
	v_mfma_f32_32x32x16_bf16 v[32:47], v[12:15], v[72:75], v[32:47]
	ds_read_b128 v[12:15], v20 offset:37984
	s_waitcnt lgkmcnt(1)
	v_mfma_f32_32x32x16_bf16 v[32:47], v[16:19], v[72:75], v[32:47]
	ds_read_b128 v[16:19], v20 offset:40288
	s_waitcnt vmcnt(1) lgkmcnt(1)
	v_mfma_f32_32x32x16_bf16 v[32:47], v[12:15], v[76:79], v[32:47]
	v_and_b32_e32 v12, 64, v203
	v_add_u32_e32 v12, 64, v12
	v_cmp_lt_i32_e32 vcc, v9, v12
	s_nop 1
	v_cndmask_b32_e32 v9, v203, v9, vcc
	v_lshlrev_b32_e32 v93, 2, v9
	s_waitcnt lgkmcnt(0)
	v_mfma_f32_32x32x16_bf16 v[32:47], v[16:19], v[76:79], v[32:47]
	s_nop 11
	ds_bpermute_b32 v42, v93, v32
	ds_bpermute_b32 v50, v93, v33
	ds_bpermute_b32 v49, v93, v34
	ds_bpermute_b32 v47, v93, v35
	ds_bpermute_b32 v46, v93, v36
	ds_bpermute_b32 v45, v93, v37
	ds_bpermute_b32 v43, v93, v38
	ds_bpermute_b32 v44, v93, v39
	s_cbranch_scc1 .LBB0_516
	v_mul_lo_u32 v104, v8, s39
	s_or_b32 s4, s96, 64
	v_add3_u32 v8, 0, v104, v92
	s_lshl_b64 s[6:7], s[4:5], 11
	ds_write_b128 v8, v[0:3]
	s_waitcnt vmcnt(0)
	ds_write_b128 v8, v[4:7] offset:9216
	v_lshl_add_u64 v[0:1], v[94:95], 0, s[6:7]
	s_mov_b32 s97, s5
	s_waitcnt lgkmcnt(0)
	s_barrier
	v_lshl_add_u64 v[2:3], s[96:97], 1, v[96:97]
	global_load_dwordx4 v[80:83], v[0:1], off
	global_load_dwordx4 v[84:87], v[2:3], off offset:128
	s_add_i32 s6, s96, 0x80
	s_mov_b32 s7, s5
	s_lshl_b64 s[6:7], s[6:7], 11
	v_lshl_add_u64 v[0:1], v[94:95], 0, s[6:7]
	global_load_dwordx4 v[160:163], v[0:1], off
	global_load_dwordx4 v[164:167], v[2:3], off offset:256
	v_lshlrev_b32_e32 v1, 1, v11
	v_lshrrev_b32_e32 v2, 1, v10
	v_and_b32_e32 v0, 19, v10
	v_and_b32_e32 v1, 8, v1
	v_and_b32_e32 v2, 4, v2
	s_sub_i32 s4, s1, 63
	v_or3_b32 v0, v2, v0, v1
	v_mul_u32_u24_e32 v105, 0x90, v0
	s_cmp_lt_i32 s38, 0
	v_mul_u32_u24_e32 v106, 0x90, v11
	s_cbranch_scc1 .LBB0_530
	v_add3_u32 v1, 0, v105, v144
	ds_read_b128 v[52:55], v1 offset:0
	ds_read_b128 v[56:59], v1 offset:4608
	ds_read_b128 v[60:63], v1 offset:32
	ds_read_b128 v[100:103], v1 offset:4640
	ds_read_b128 v[108:111], v1 offset:64
	ds_read_b128 v[112:115], v1 offset:4672
	s_sub_i32 s1, s4, s96
	ds_read_b128 v[116:119], v1 offset:96
	s_cmpk_gt_i32 s1, 0x7f
	ds_read_b128 v[120:123], v1 offset:4704
	s_cselect_b64 vcc, -1, 0
	v_cndmask_b32_e32 v0, 0, v99, vcc
	v_mov_b32_e32 v1, v0
	v_mov_b64_e32 v[2:3], v[0:1]
	v_mov_b64_e32 v[4:5], v[0:1]
	v_mov_b64_e32 v[6:7], v[0:1]
	v_mov_b64_e32 v[8:9], v[0:1]
	v_mov_b64_e32 v[10:11], v[0:1]
	v_mov_b64_e32 v[12:13], v[0:1]
	v_mov_b64_e32 v[14:15], v[0:1]
	s_waitcnt lgkmcnt(6)
	s_nop 1
	v_mfma_f32_32x32x16_bf16 v[16:31], v[52:55], v[64:67], v[0:15]
	s_and_b64 vcc, exec, vcc
	v_mfma_f32_32x32x16_bf16 v[0:15], v[56:59], v[64:67], v[0:15]
	s_waitcnt lgkmcnt(4)
	v_mfma_f32_32x32x16_bf16 v[16:31], v[60:63], v[68:71], v[16:31]
	v_mfma_f32_32x32x16_bf16 v[0:15], v[100:103], v[68:71], v[0:15]
	s_waitcnt lgkmcnt(2)
	v_mfma_f32_32x32x16_bf16 v[16:31], v[108:111], v[72:75], v[16:31]
	v_mfma_f32_32x32x16_bf16 v[0:15], v[112:115], v[72:75], v[0:15]
	s_waitcnt lgkmcnt(0)
	v_mfma_f32_32x32x16_bf16 v[16:31], v[116:119], v[76:79], v[16:31]
	v_mfma_f32_32x32x16_bf16 v[0:15], v[120:123], v[76:79], v[0:15]
	s_cbranch_vccnz .LBB0_528
; #define ALAS __attribute__((address_space(3)))
; __device__ __forceinline__ void near_bias(f32x16& s0, f32x16& s1, const ALAS float* bt, int qpos, int kbase, int hi) {
; #pragma unroll
;     for (int r = 0; r < 16; ++r) {
;         const int d0 = qpos - (kbase + (r & 7) + 8 * hi + 16 * (r >> 3)), d1 = d0 - 32;
;         const float b0 = bt[min(max(d0, 0), 255)], b1 = bt[min(max(d1, 0), 255)];
;         s0[r] = d0 < 0 ? NEG : s0[r] + b0; s1[r] = d1 < 0 ? NEG : s1[r] + b1;
;     }
; }
	v_or_b32_e32 v51, s96, v98
	v_xad_u32 v107, v51, -1, v90
	v_med3_i32 v52, v107, 0, v204
	v_lshl_add_u32 v53, v52, 2, 0
	v_max_i32_e32 v52, 32, v107
	v_subrev_u32_e32 v52, 32, v52
	v_min_u32_e32 v52, 0xff, v52
	v_or_b32_e32 v55, 2, v51
	v_lshl_add_u32 v54, v52, 2, 0
	v_or_b32_e32 v52, 3, v51
	v_sub_u32_e32 v123, v90, v55
	v_sub_u32_e32 v122, v90, v52
	v_med3_i32 v52, v123, 0, v204
	v_lshl_add_u32 v55, v52, 2, 0
	v_max_i32_e32 v52, 32, v123
	v_subrev_u32_e32 v52, 32, v52
	v_min_u32_e32 v52, 0xff, v52
	v_sub_u32_e32 v91, v90, v51
	v_lshl_add_u32 v56, v52, 2, 0
	v_max_i32_e32 v52, 32, v122
	v_max_i32_e32 v41, 32, v91
	v_subrev_u32_e32 v52, 32, v52
	v_subrev_u32_e32 v41, 32, v41
	v_min_u32_e32 v52, 0xff, v52
	v_med3_i32 v40, v91, 0, v204
	v_min_u32_e32 v41, 0xff, v41
	v_lshl_add_u32 v57, v52, 2, 0
	v_med3_i32 v52, v122, 0, v204
	v_lshl_add_u32 v40, v40, 2, 0
	v_lshl_add_u32 v41, v41, 2, 0
	v_lshl_add_u32 v58, v52, 2, 0
	ds_read_b32 v52, v40 offset:36864
	ds_read_b32 v40, v41 offset:36864
	ds_read_b32 v53, v53 offset:36864
	ds_read_b32 v41, v54 offset:36864
	ds_read_b32 v54, v55 offset:36864
	ds_read_b32 v56, v56 offset:36864
	ds_read_b32 v57, v57 offset:36864
	ds_read_b32 v55, v58 offset:36864
	v_or_b32_e32 v58, 5, v51
	v_sub_u32_e32 v124, v90, v58
	v_max_i32_e32 v60, 32, v124
	v_subrev_u32_e32 v60, 32, v60
	v_min_u32_e32 v60, 0xff, v60
	v_lshl_add_u32 v61, v60, 2, 0
	v_med3_i32 v60, v124, 0, v204
	v_or_b32_e32 v63, 6, v51
	v_lshl_add_u32 v62, v60, 2, 0
	v_or_b32_e32 v60, 7, v51
	v_sub_u32_e32 v127, v90, v63
	v_sub_u32_e32 v126, v90, v60
	v_med3_i32 v60, v127, 0, v204
	v_lshl_add_u32 v63, v60, 2, 0
	v_max_i32_e32 v60, 32, v127
	v_subrev_u32_e32 v60, 32, v60
	v_or_b32_e32 v59, 4, v51
	v_min_u32_e32 v60, 0xff, v60
	v_sub_u32_e32 v125, v90, v59
	v_lshl_add_u32 v100, v60, 2, 0
	v_max_i32_e32 v60, 32, v126
	v_max_i32_e32 v59, 32, v125
	v_subrev_u32_e32 v60, 32, v60
	v_subrev_u32_e32 v59, 32, v59
	v_min_u32_e32 v60, 0xff, v60
	v_med3_i32 v58, v125, 0, v204
	v_min_u32_e32 v59, 0xff, v59
	v_lshl_add_u32 v101, v60, 2, 0
	v_med3_i32 v60, v126, 0, v204
	v_lshl_add_u32 v58, v58, 2, 0
	v_lshl_add_u32 v59, v59, 2, 0
	v_lshl_add_u32 v102, v60, 2, 0
	ds_read_b32 v58, v58 offset:36864
	ds_read_b32 v60, v59 offset:36864
	ds_read_b32 v61, v61 offset:36864
	ds_read_b32 v59, v62 offset:36864
	ds_read_b32 v62, v63 offset:36864
	ds_read_b32 v100, v100 offset:36864
	ds_read_b32 v101, v101 offset:36864
	ds_read_b32 v63, v102 offset:36864
	v_or_b32_e32 v102, 17, v51
	v_sub_u32_e32 v128, v90, v102
	v_max_i32_e32 v108, 32, v128
	v_subrev_u32_e32 v108, 32, v108
	v_min_u32_e32 v108, 0xff, v108
	v_lshl_add_u32 v109, v108, 2, 0
	v_med3_i32 v108, v128, 0, v204
	v_or_b32_e32 v111, 18, v51
	v_lshl_add_u32 v110, v108, 2, 0
	v_or_b32_e32 v108, 19, v51
	v_sub_u32_e32 v131, v90, v111
	v_sub_u32_e32 v130, v90, v108
	v_med3_i32 v108, v131, 0, v204
	v_lshl_add_u32 v111, v108, 2, 0
	v_max_i32_e32 v108, 32, v131
	v_subrev_u32_e32 v108, 32, v108
	v_or_b32_e32 v103, 16, v51
	v_min_u32_e32 v108, 0xff, v108
	v_sub_u32_e32 v129, v90, v103
	v_lshl_add_u32 v112, v108, 2, 0
	v_max_i32_e32 v108, 32, v130
	v_max_i32_e32 v103, 32, v129
	v_subrev_u32_e32 v108, 32, v108
	v_subrev_u32_e32 v103, 32, v103
	v_min_u32_e32 v108, 0xff, v108
	v_med3_i32 v102, v129, 0, v204
	v_min_u32_e32 v103, 0xff, v103
	v_lshl_add_u32 v113, v108, 2, 0
	v_med3_i32 v108, v130, 0, v204
	v_lshl_add_u32 v102, v102, 2, 0
	v_lshl_add_u32 v103, v103, 2, 0
	v_lshl_add_u32 v114, v108, 2, 0
	ds_read_b32 v102, v102 offset:36864
	ds_read_b32 v108, v103 offset:36864
	ds_read_b32 v109, v109 offset:36864
	ds_read_b32 v103, v110 offset:36864
	ds_read_b32 v110, v111 offset:36864
	ds_read_b32 v112, v112 offset:36864
	ds_read_b32 v113, v113 offset:36864
	ds_read_b32 v111, v114 offset:36864
	v_or_b32_e32 v114, 21, v51
	v_sub_u32_e32 v132, v90, v114
	v_max_i32_e32 v116, 32, v132
	v_subrev_u32_e32 v116, 32, v116
	v_min_u32_e32 v116, 0xff, v116
	v_lshl_add_u32 v117, v116, 2, 0
	v_med3_i32 v116, v132, 0, v204
	v_or_b32_e32 v115, 20, v51
	v_lshl_add_u32 v118, v116, 2, 0
	v_or_b32_e32 v116, 23, v51
	v_or_b32_e32 v51, 22, v51
	v_sub_u32_e32 v51, v90, v51
	v_sub_u32_e32 v134, v90, v116
	v_med3_i32 v116, v51, 0, v204
	v_lshl_add_u32 v119, v116, 2, 0
	v_max_i32_e32 v116, 32, v51
	v_subrev_u32_e32 v116, 32, v116
	v_sub_u32_e32 v133, v90, v115
	v_min_u32_e32 v116, 0xff, v116
	v_max_i32_e32 v115, 32, v133
	v_lshl_add_u32 v120, v116, 2, 0
	v_max_i32_e32 v116, 32, v134
	v_subrev_u32_e32 v115, 32, v115
	v_subrev_u32_e32 v116, 32, v116
	v_med3_i32 v114, v133, 0, v204
	v_min_u32_e32 v115, 0xff, v115
	v_min_u32_e32 v116, 0xff, v116
	v_lshl_add_u32 v114, v114, 2, 0
	v_lshl_add_u32 v115, v115, 2, 0
	v_lshl_add_u32 v121, v116, 2, 0
	v_med3_i32 v116, v134, 0, v204
	v_lshl_add_u32 v135, v116, 2, 0
	ds_read_b32 v114, v114 offset:36864
	ds_read_b32 v116, v115 offset:36864
	ds_read_b32 v117, v117 offset:36864
	ds_read_b32 v115, v118 offset:36864
	ds_read_b32 v118, v119 offset:36864
	ds_read_b32 v120, v120 offset:36864
	ds_read_b32 v121, v121 offset:36864
	ds_read_b32 v119, v135 offset:36864
	v_cmp_lt_i32_e32 vcc, -1, v134
	s_waitcnt lgkmcnt(4)
; #define ALAS __attribute__((address_space(3)))
; __device__ __forceinline__ void near_bias(f32x16& s0, f32x16& s1, const ALAS float* bt, int qpos, int kbase, int hi) {
; #pragma unroll
;     for (int r = 0; r < 16; ++r) {
;         const int d0 = qpos - (kbase + (r & 7) + 8 * hi + 16 * (r >> 3)), d1 = d0 - 32;
;         const float b0 = bt[min(max(d0, 0), 255)], b1 = bt[min(max(d1, 0), 255)];
;         s0[r] = d0 < 0 ? NEG : s0[r] + b0; s1[r] = d1 < 0 ? NEG : s1[r] + b1;
;     }
; }
	v_pk_add_f32 v[28:29], v[28:29], v[114:115]
	v_pk_add_f32 v[26:27], v[26:27], v[110:111]
	v_pk_add_f32 v[24:25], v[24:25], v[102:103]
	s_waitcnt lgkmcnt(0)
	v_pk_add_f32 v[30:31], v[30:31], v[118:119]
	v_pk_add_f32 v[22:23], v[22:23], v[62:63]
	v_cndmask_b32_e32 v31, v205, v31, vcc
	v_cmp_lt_i32_e32 vcc, -1, v51
	v_pk_add_f32 v[20:21], v[20:21], v[58:59]
	v_pk_add_f32 v[18:19], v[18:19], v[54:55]
	v_cndmask_b32_e32 v30, v205, v30, vcc
	v_cmp_lt_i32_e32 vcc, -1, v132
	v_pk_add_f32 v[16:17], v[16:17], v[52:53]
	v_pk_add_f32 v[14:15], v[14:15], v[120:121]
	v_cndmask_b32_e32 v29, v205, v29, vcc
	v_cmp_lt_i32_e32 vcc, -1, v133
	v_pk_add_f32 v[12:13], v[12:13], v[116:117]
	v_pk_add_f32 v[10:11], v[10:11], v[112:113]
	v_cndmask_b32_e32 v28, v205, v28, vcc
	v_cmp_lt_i32_e32 vcc, -1, v130
	v_pk_add_f32 v[8:9], v[8:9], v[108:109]
	v_pk_add_f32 v[6:7], v[6:7], v[100:101]
	v_cndmask_b32_e32 v27, v205, v27, vcc
	v_cmp_lt_i32_e32 vcc, -1, v131
	v_pk_add_f32 v[4:5], v[4:5], v[60:61]
	v_pk_add_f32 v[2:3], v[2:3], v[56:57]
	v_cndmask_b32_e32 v26, v205, v26, vcc
	v_cmp_lt_i32_e32 vcc, -1, v128
	v_pk_add_f32 v[0:1], v[0:1], v[40:41]
	s_nop 0
	v_cndmask_b32_e32 v25, v205, v25, vcc
	v_cmp_lt_i32_e32 vcc, -1, v129
	s_nop 1
	v_cndmask_b32_e32 v24, v205, v24, vcc
	v_cmp_lt_i32_e32 vcc, -1, v126
	s_nop 1
	v_cndmask_b32_e32 v23, v205, v23, vcc
	v_cmp_lt_i32_e32 vcc, -1, v127
	s_nop 1
	v_cndmask_b32_e32 v22, v205, v22, vcc
	v_cmp_lt_i32_e32 vcc, -1, v124
	s_nop 1
	v_cndmask_b32_e32 v21, v205, v21, vcc
	v_cmp_lt_i32_e32 vcc, -1, v125
	s_nop 1
	v_cndmask_b32_e32 v20, v205, v20, vcc
	v_cmp_lt_i32_e32 vcc, -1, v122
	s_nop 1
	v_cndmask_b32_e32 v19, v205, v19, vcc
	v_cmp_lt_i32_e32 vcc, -1, v123
	s_nop 1
	v_cndmask_b32_e32 v18, v205, v18, vcc
	v_cmp_lt_i32_e32 vcc, -1, v107
	s_nop 1
	v_cndmask_b32_e32 v17, v205, v17, vcc
	v_cmp_lt_i32_e32 vcc, -1, v91
	s_nop 1
	v_cndmask_b32_e32 v16, v205, v16, vcc
	v_cmp_lt_i32_e32 vcc, 31, v134
	s_nop 1
	v_cndmask_b32_e32 v15, v205, v15, vcc
	v_cmp_lt_i32_e32 vcc, 31, v51
	s_nop 1
	v_cndmask_b32_e32 v14, v205, v14, vcc
	v_cmp_lt_i32_e32 vcc, 31, v132
	s_nop 1
	v_cndmask_b32_e32 v13, v205, v13, vcc
	v_cmp_lt_i32_e32 vcc, 31, v133
	s_nop 1
	v_cndmask_b32_e32 v12, v205, v12, vcc
	v_cmp_lt_i32_e32 vcc, 31, v130
	s_nop 1
	v_cndmask_b32_e32 v11, v205, v11, vcc
	v_cmp_lt_i32_e32 vcc, 31, v131
	s_nop 1
	v_cndmask_b32_e32 v10, v205, v10, vcc
	v_cmp_lt_i32_e32 vcc, 31, v128
	s_nop 1
	v_cndmask_b32_e32 v9, v205, v9, vcc
	v_cmp_lt_i32_e32 vcc, 31, v129
	s_nop 1
	v_cndmask_b32_e32 v8, v205, v8, vcc
	v_cmp_lt_i32_e32 vcc, 31, v126
	s_nop 1
	v_cndmask_b32_e32 v7, v205, v7, vcc
	v_cmp_lt_i32_e32 vcc, 31, v127
	s_nop 1
	v_cndmask_b32_e32 v6, v205, v6, vcc
	v_cmp_lt_i32_e32 vcc, 31, v124
	s_nop 1
	v_cndmask_b32_e32 v5, v205, v5, vcc
	v_cmp_lt_i32_e32 vcc, 31, v125
	s_nop 1
	v_cndmask_b32_e32 v4, v205, v4, vcc
	v_cmp_lt_i32_e32 vcc, 31, v122
	s_nop 1
	v_cndmask_b32_e32 v3, v205, v3, vcc
	v_cmp_lt_i32_e32 vcc, 31, v123
	s_nop 1
	v_cndmask_b32_e32 v2, v205, v2, vcc
	v_cmp_lt_i32_e32 vcc, 31, v107
	s_nop 1
	v_cndmask_b32_e32 v1, v205, v1, vcc
	v_cmp_lt_i32_e32 vcc, 31, v91
	s_nop 1
	v_cndmask_b32_e32 v0, v205, v0, vcc

; #define ALAS __attribute__((address_space(3)))
; __device__ __forceinline__ int kperm(int i) { return (i & 19) | ((i & 4) << 1) | ((i & 8) >> 1); }
; template <int OFF> __device__ __forceinline__ void ldsr(bf16x8& d, unsigned a) { asm volatile("ds_read_b128 %0, %1 offset:%c2" : "=v"(d) : "v"(a), "i"(OFF) : "memory"); }
; __device__ __forceinline__ void lds_wait8(bf16x8 (&a)[8]) { asm volatile("s_waitcnt lgkmcnt(0)" : "+v"(a[0]), "+v"(a[1]), "+v"(a[2]), "+v"(a[3]), "+v"(a[4]), "+v"(a[5]), "+v"(a[6]), "+v"(a[7]) :: "memory"); }
; __device__ __forceinline__ void qk_tile(f32x16& s0, f32x16& s1, float ci, const ALAS unsigned char* Kb, const bf16x8 (&qf)[4], int r32, int hi) {
;     const unsigned p0 = (unsigned)(uintptr_t)(Kb + kperm(r32) * ROWB + hi * 16);
;     bf16x8 a[8];
;     ldsr<0>(a[0], p0); ldsr<32 * ROWB>(a[1], p0); ldsr<32>(a[2], p0); ldsr<32 * ROWB + 32>(a[3], p0);
;     ldsr<64>(a[4], p0); ldsr<32 * ROWB + 64>(a[5], p0); ldsr<96>(a[6], p0); ldsr<32 * ROWB + 96>(a[7], p0);
; #pragma unroll
;     for (int r = 0; r < 16; ++r) { s0[r] = ci; s1[r] = ci; }
;     lds_wait8(a); __builtin_amdgcn_sched_barrier(0);
; #pragma unroll
;     for (int d0 = 0; d0 < 4; ++d0) {
;         s0 = __builtin_amdgcn_mfma_f32_32x32x16_bf16(a[2 * d0], qf[d0], s0, 0, 0, 0);
;         s1 = __builtin_amdgcn_mfma_f32_32x32x16_bf16(a[2 * d0 + 1], qf[d0], s1, 0, 0, 0);
;     }
; __device__ __forceinline__ void moba_unit(int b, int h, int j, const bf16_t* Q, const bf16_t* K, const bf16_t* VT, bf16_t* O, const float* biasd, const float* kmean, ALAS unsigned char* lds) {
;     ...
;         const bool own = t < 4; const int n = own ? j : ((t - 4) >> 2); const int kbase = own ? (256 * j + 64 * t) : (64 * (t - 4));
;         const bool sel = own ? true : (((selmask >> n) & 1u) != 0u);
;         const bool active = own ? (64 * t <= 32 * wid + 31) : (__any(sel) != 0);
;         if (active) {
;             const bool nearb = (q0 - (kbase + 63)) < 128;
;             f32x16 s0, s1; const float ci = sel ? ((nearb ? 0.f : cb) - mref) : NEG;
;             qk_tile(s0, s1, ci, buf, qf, r32, hi);
;             if (nearb) near_bias(s0, s1, bt, qpos, kbase, hi);
.Lmb_542b:
	s_add_i32 s10, s18, 0x100
	s_and_b64 s[8:9], s[6:7], exec
	s_cselect_b32 s8, s10, s15
	s_or_b64 vcc, s[6:7], s[0:1]
	s_sub_i32 s0, s4, s8
	s_cmpk_gt_i32 s0, 0x7f
	s_cselect_b64 s[0:1], -1, 0
	v_cndmask_b32_e64 v32, 0, v99, s[0:1]
	v_sub_f32_e32 v32, v32, v101
	v_cndmask_b32_e32 v32, v205, v32, vcc
	v_mov_b32_e32 v33, v32
	v_mov_b64_e32 v[34:35], v[32:33]
	v_mov_b64_e32 v[36:37], v[32:33]
	v_mov_b64_e32 v[38:39], v[32:33]
	v_mov_b64_e32 v[40:41], v[32:33]
	v_mov_b64_e32 v[42:43], v[32:33]
	v_mov_b64_e32 v[44:45], v[32:33]
	v_mov_b64_e32 v[46:47], v[32:33]
	s_waitcnt lgkmcnt(6)
	s_nop 1
	v_mfma_f32_32x32x16_bf16 v[48:63], v[108:111], v[64:67], v[32:47]
	s_and_b64 vcc, exec, s[0:1]
	v_mfma_f32_32x32x16_bf16 v[32:47], v[112:115], v[64:67], v[32:47]
	s_waitcnt lgkmcnt(4)
	v_mfma_f32_32x32x16_bf16 v[48:63], v[116:119], v[68:71], v[48:63]
	v_mfma_f32_32x32x16_bf16 v[32:47], v[120:123], v[68:71], v[32:47]
	s_waitcnt lgkmcnt(2)
	v_mfma_f32_32x32x16_bf16 v[48:63], v[124:127], v[72:75], v[48:63]
	v_mfma_f32_32x32x16_bf16 v[32:47], v[128:131], v[72:75], v[32:47]
	s_waitcnt lgkmcnt(0)
	v_mfma_f32_32x32x16_bf16 v[48:63], v[132:135], v[76:79], v[48:63]
	v_mfma_f32_32x32x16_bf16 v[32:47], v[136:139], v[76:79], v[32:47]
	s_cbranch_vccnz .Lmb_544b
	v_or_b32_e32 v140, s8, v98
	v_sub_u32_e32 v140, v90, v140
	v_lshlrev_b32_e32 v140, 2, v140
	v_add_u32_e32 v140, 0xab24, v140
	ds_read_b32 v108, v140 offset:92
	ds_read_b32 v109, v140 offset:88
	ds_read_b32 v110, v140 offset:84
	ds_read_b32 v111, v140 offset:80
	ds_read_b32 v112, v140 offset:76
	ds_read_b32 v113, v140 offset:72
	ds_read_b32 v114, v140 offset:68
	ds_read_b32 v115, v140 offset:64
	ds_read_b32 v116, v140 offset:28
	ds_read_b32 v117, v140 offset:24
	ds_read_b32 v118, v140 offset:20
	ds_read_b32 v119, v140 offset:16
	ds_read_b32 v120, v140 offset:12
	ds_read_b32 v121, v140 offset:8
	ds_read_b32 v122, v140 offset:4
	ds_read_b32 v123, v140 offset:0
	ds_read_b32 v124, v140 offset:220
	ds_read_b32 v125, v140 offset:216
	ds_read_b32 v126, v140 offset:212
	ds_read_b32 v127, v140 offset:208
	ds_read_b32 v128, v140 offset:204
	ds_read_b32 v129, v140 offset:200
	ds_read_b32 v130, v140 offset:196
	ds_read_b32 v131, v140 offset:192
	ds_read_b32 v132, v140 offset:156
	ds_read_b32 v133, v140 offset:152
	ds_read_b32 v134, v140 offset:148
	ds_read_b32 v135, v140 offset:144
	ds_read_b32 v136, v140 offset:140
	ds_read_b32 v137, v140 offset:136
	ds_read_b32 v138, v140 offset:132
	ds_read_b32 v139, v140 offset:128
	s_waitcnt lgkmcnt(0)
	v_add_f32_e32 v32, v32, v108
	v_add_f32_e32 v33, v33, v109
	v_add_f32_e32 v34, v34, v110
	v_add_f32_e32 v35, v35, v111
	v_add_f32_e32 v36, v36, v112
	v_add_f32_e32 v37, v37, v113
	v_add_f32_e32 v38, v38, v114
	v_add_f32_e32 v39, v39, v115
	v_add_f32_e32 v40, v40, v116
	v_add_f32_e32 v41, v41, v117
	v_add_f32_e32 v42, v42, v118
	v_add_f32_e32 v43, v43, v119
	v_add_f32_e32 v44, v44, v120
	v_add_f32_e32 v45, v45, v121
	v_add_f32_e32 v46, v46, v122
	v_add_f32_e32 v47, v47, v123
	v_add_f32_e32 v48, v48, v124
	v_add_f32_e32 v49, v49, v125
	v_add_f32_e32 v50, v50, v126
	v_add_f32_e32 v51, v51, v127
	v_add_f32_e32 v52, v52, v128
	v_add_f32_e32 v53, v53, v129
	v_add_f32_e32 v54, v54, v130
	v_add_f32_e32 v55, v55, v131
	v_add_f32_e32 v56, v56, v132
	v_add_f32_e32 v57, v57, v133
	v_add_f32_e32 v58, v58, v134
	v_add_f32_e32 v59, v59, v135
	v_add_f32_e32 v60, v60, v136
	v_add_f32_e32 v61, v61, v137
	v_add_f32_e32 v62, v62, v138
	v_add_f32_e32 v63, v63, v139
